# NSA tile loops: probability sum tree interleaved with the last PV MFMAs instead of after them (on top of the in-place packed subtract)
# baseline (speedup 1.0000x reference)
; #define LAS __attribute__((address_space(3)))
; __device__ __forceinline__ unsigned cvtpk(float lo, float hi) { f32x2v_ v = {lo, hi}; bf16x2v_ b = __builtin_convertvector(v, bf16x2v_); return __builtin_bit_cast(unsigned, b); }
; __device__ __forceinline__ void nsa_pv(f32x16& o0, f32x16& o1, const f32x16& p0, const f32x16& p1, const LAS unsigned char* vslot, int lane, int hi) {
;     u32x4 pw[4];
; #pragma unroll
;     for (int k = 0; k < 4; ++k) { pw[0][k] = cvtpk(p0[2 * k], p0[2 * k + 1]); pw[1][k] = cvtpk(p0[8 + 2 * k], p0[9 + 2 * k]); pw[2][k] = cvtpk(p1[2 * k], p1[2 * k + 1]); pw[3][k] = cvtpk(p1[8 + 2 * k], p1[9 + 2 * k]); }
;     const LAS unsigned char* vp = vslot + ((lane >> 4) & 1) * 32 + (lane & 3) * 8 + (4 * hi + ((lane & 15) >> 2)) * 64;
; #pragma unroll
;     for (int ks = 0; ks < 4; ++ks) {
;         const s16x4v a0 = __builtin_bit_cast(s16x4v, __builtin_amdgcn_ds_read_tr16_b64_v4i16((LAS s16x4v*)(vp + ks * 1024)));
;         const s16x4v a1 = __builtin_bit_cast(s16x4v, __builtin_amdgcn_ds_read_tr16_b64_v4i16((LAS s16x4v*)(vp + ks * 1024 + 512)));
;         const s16x4v b0 = __builtin_bit_cast(s16x4v, __builtin_amdgcn_ds_read_tr16_b64_v4i16((LAS s16x4v*)(vp + 4096 + ks * 1024)));
;         const s16x4v b1 = __builtin_bit_cast(s16x4v, __builtin_amdgcn_ds_read_tr16_b64_v4i16((LAS s16x4v*)(vp + 4096 + ks * 1024 + 512)));
;         const bf16x8v va = {a0[0], a0[1], a0[2], a0[3], a1[0], a1[1], a1[2], a1[3]}, vb = {b0[0], b0[1], b0[2], b0[3], b1[0], b1[1], b1[2], b1[3]};
;         const bf16x8v pa = __builtin_bit_cast(bf16x8v, pw[ks]);
;         o0 = __builtin_amdgcn_mfma_f32_32x32x16_bf16(pa, va, o0, 0, 0, 0); o1 = __builtin_amdgcn_mfma_f32_32x32x16_bf16(pa, vb, o1, 0, 0, 0); }
; }
; __device__ __forceinline__ void nsa_softmax_pv(NsaSm& st, f32x16& p0, f32x16& p1, const LAS unsigned char* vslot, LAS float* wsf, int lane, int r32, int hi, bool on = true) {
;     const float rmx = rowmax32(p0, p1); const float rm = on ? rmx : SNEG; const float mn = fmaxf(st.m, rm); const float f = __builtin_amdgcn_exp2f(st.m - mn); st.m = mn;
;     const float cs = on ? mn : 1.0e30f;
;     float s = 0.f;
; #pragma unroll
;     for (int r = 0; r < 16; ++r) { p0[r] = __builtin_amdgcn_exp2f(p0[r] - cs); p1[r] = __builtin_amdgcn_exp2f(p1[r] - cs); s += p0[r] + p1[r]; }
;     st.l = st.l * f + s;
.LBB0_1333:
	v_mov_b32_e32 v2, 0x7149f2ca
	v_cndmask_b32_e64 v2, v2, v0, s[16:17]
	v_pk_add_f32 v[80:81], v[80:81], v[2:3] op_sel_hi:[1,0] neg_lo:[0,1] neg_hi:[0,1]
	v_pk_add_f32 v[82:83], v[82:83], v[2:3] op_sel_hi:[1,0] neg_lo:[0,1] neg_hi:[0,1]
	v_pk_add_f32 v[84:85], v[84:85], v[2:3] op_sel_hi:[1,0] neg_lo:[0,1] neg_hi:[0,1]
	v_pk_add_f32 v[86:87], v[86:87], v[2:3] op_sel_hi:[1,0] neg_lo:[0,1] neg_hi:[0,1]
	v_pk_add_f32 v[88:89], v[88:89], v[2:3] op_sel_hi:[1,0] neg_lo:[0,1] neg_hi:[0,1]
	v_pk_add_f32 v[90:91], v[90:91], v[2:3] op_sel_hi:[1,0] neg_lo:[0,1] neg_hi:[0,1]
	v_pk_add_f32 v[92:93], v[92:93], v[2:3] op_sel_hi:[1,0] neg_lo:[0,1] neg_hi:[0,1]
	v_pk_add_f32 v[94:95], v[94:95], v[2:3] op_sel_hi:[1,0] neg_lo:[0,1] neg_hi:[0,1]
	v_pk_add_f32 v[128:129], v[128:129], v[2:3] op_sel_hi:[1,0] neg_lo:[0,1] neg_hi:[0,1]
	v_pk_add_f32 v[130:131], v[130:131], v[2:3] op_sel_hi:[1,0] neg_lo:[0,1] neg_hi:[0,1]
	v_pk_add_f32 v[132:133], v[132:133], v[2:3] op_sel_hi:[1,0] neg_lo:[0,1] neg_hi:[0,1]
	v_pk_add_f32 v[134:135], v[134:135], v[2:3] op_sel_hi:[1,0] neg_lo:[0,1] neg_hi:[0,1]
	v_pk_add_f32 v[136:137], v[136:137], v[2:3] op_sel_hi:[1,0] neg_lo:[0,1] neg_hi:[0,1]
	v_pk_add_f32 v[138:139], v[138:139], v[2:3] op_sel_hi:[1,0] neg_lo:[0,1] neg_hi:[0,1]
	v_pk_add_f32 v[140:141], v[140:141], v[2:3] op_sel_hi:[1,0] neg_lo:[0,1] neg_hi:[0,1]
	v_pk_add_f32 v[142:143], v[142:143], v[2:3] op_sel_hi:[1,0] neg_lo:[0,1] neg_hi:[0,1]
	v_exp_f32_e32 v80, v80
	v_exp_f32_e32 v81, v81
	v_exp_f32_e32 v82, v82
	v_exp_f32_e32 v83, v83
	v_exp_f32_e32 v84, v84
	v_exp_f32_e32 v85, v85
	v_exp_f32_e32 v86, v86
	v_exp_f32_e32 v87, v87
	v_add_u32_e32 v103, s20, v238
	v_cvt_pk_bf16_f32 v104, v80, v81
	v_cvt_pk_bf16_f32 v105, v82, v83
	v_cvt_pk_bf16_f32 v106, v84, v85
	v_cvt_pk_bf16_f32 v107, v86, v87
	ds_read_b64_tr_b16 v[116:117], v103 offset:17408
	ds_read_b64_tr_b16 v[118:119], v103 offset:17920
	ds_read_b64_tr_b16 v[120:121], v103 offset:21504
	ds_read_b64_tr_b16 v[122:123], v103 offset:22016
	v_exp_f32_e32 v88, v88
	v_exp_f32_e32 v89, v89
	v_exp_f32_e32 v90, v90
	v_exp_f32_e32 v91, v91
	v_exp_f32_e32 v92, v92
	v_exp_f32_e32 v93, v93
	v_exp_f32_e32 v94, v94
	v_exp_f32_e32 v95, v95
	v_exp_f32_e32 v128, v128
	v_exp_f32_e32 v129, v129
	v_exp_f32_e32 v130, v130
	v_exp_f32_e32 v131, v131
	v_exp_f32_e32 v132, v132
	v_exp_f32_e32 v133, v133
	v_exp_f32_e32 v134, v134
	v_exp_f32_e32 v135, v135
	s_waitcnt lgkmcnt(2)
	v_mfma_f32_32x32x16_bf16 v[64:79], v[104:107], v[116:119], v[64:79]
	v_cvt_pk_bf16_f32 v108, v88, v89
	v_cvt_pk_bf16_f32 v109, v90, v91
	v_cvt_pk_bf16_f32 v110, v92, v93
	v_cvt_pk_bf16_f32 v111, v94, v95
	v_cvt_pk_bf16_f32 v112, v128, v129
	v_cvt_pk_bf16_f32 v113, v130, v131
	v_cvt_pk_bf16_f32 v114, v132, v133
	s_waitcnt lgkmcnt(0)
	v_mfma_f32_32x32x16_bf16 v[48:63], v[104:107], v[120:123], v[48:63]
	ds_read_b64_tr_b16 v[104:105], v103 offset:18432
	ds_read_b64_tr_b16 v[106:107], v103 offset:18944
	ds_read_b64_tr_b16 v[116:117], v103 offset:22528
	ds_read_b64_tr_b16 v[118:119], v103 offset:23040
	v_cvt_pk_bf16_f32 v115, v134, v135
	v_exp_f32_e32 v136, v136
	v_exp_f32_e32 v137, v137
	v_exp_f32_e32 v138, v138
	v_exp_f32_e32 v139, v139
	v_exp_f32_e32 v140, v140
	v_exp_f32_e32 v141, v141
	v_exp_f32_e32 v142, v142
	v_exp_f32_e32 v143, v143
	v_cvt_pk_bf16_f32 v2, v136, v137
	v_cvt_pk_bf16_f32 v3, v138, v139
	v_cvt_pk_bf16_f32 v4, v140, v141
	s_waitcnt lgkmcnt(2)
	v_mfma_f32_32x32x16_bf16 v[64:79], v[108:111], v[104:107], v[64:79]
	v_cvt_pk_bf16_f32 v5, v142, v143
	s_andn2_b64 vcc, exec, s[36:37]
	s_waitcnt lgkmcnt(0)
	v_mfma_f32_32x32x16_bf16 v[48:63], v[108:111], v[116:119], v[48:63]
	ds_read_b64_tr_b16 v[104:105], v103 offset:19456
	ds_read_b64_tr_b16 v[106:107], v103 offset:19968
	ds_read_b64_tr_b16 v[108:109], v103 offset:23552
	ds_read_b64_tr_b16 v[110:111], v103 offset:24064
	v_pk_add_f32 v[80:81], v[80:81], v[82:83]
	v_pk_add_f32 v[84:85], v[84:85], v[86:87]
	v_pk_add_f32 v[88:89], v[88:89], v[90:91]
	v_pk_add_f32 v[92:93], v[92:93], v[94:95]
	s_waitcnt lgkmcnt(2)
	v_mfma_f32_32x32x16_bf16 v[64:79], v[112:115], v[104:107], v[64:79]
	v_pk_add_f32 v[128:129], v[128:129], v[130:131]
	v_pk_add_f32 v[132:133], v[132:133], v[134:135]
	v_pk_add_f32 v[136:137], v[136:137], v[138:139]
	v_pk_add_f32 v[140:141], v[140:141], v[142:143]
	s_waitcnt lgkmcnt(0)
	v_mfma_f32_32x32x16_bf16 v[48:63], v[112:115], v[108:111], v[48:63]
	ds_read_b64_tr_b16 v[104:105], v103 offset:20480
	ds_read_b64_tr_b16 v[106:107], v103 offset:20992
	ds_read_b64_tr_b16 v[108:109], v103 offset:24576
	ds_read_b64_tr_b16 v[110:111], v103 offset:25088
	v_pk_add_f32 v[80:81], v[80:81], v[84:85]
	v_pk_add_f32 v[88:89], v[88:89], v[92:93]
	v_pk_add_f32 v[128:129], v[128:129], v[132:133]
	v_pk_add_f32 v[136:137], v[136:137], v[140:141]
	s_waitcnt lgkmcnt(2)
	v_mfma_f32_32x32x16_bf16 v[64:79], v[2:5], v[104:107], v[64:79]
	v_pk_add_f32 v[80:81], v[80:81], v[88:89]
	v_pk_add_f32 v[128:129], v[128:129], v[136:137]
	v_pk_add_f32 v[80:81], v[80:81], v[128:129]
	v_add_f32_e32 v80, v80, v81
	s_waitcnt lgkmcnt(0)
	v_mfma_f32_32x32x16_bf16 v[48:63], v[2:5], v[108:111], v[48:63]
	s_cbranch_vccnz .LBB0_1335
	s_xor_b32 s2, s20, 0x2000
	v_add_u32_e32 v2, s2, v251
	s_waitcnt vmcnt(1)
	ds_write_b128 v2, v[144:147] offset:1024
	s_waitcnt vmcnt(0)
	ds_write_b128 v2, v[148:151] offset:17408
.LBB0_1335:
	v_fma_f32 v2, v157, v6, v80
	s_andn2_b64 vcc, exec, s[6:7]
	s_xor_b32 s42, s42, 1
	s_waitcnt lgkmcnt(0)
	s_barrier
	s_cbranch_vccz .LBB0_1337
	v_mov_b32_e32 v157, v2
	v_mov_b32_e32 v158, v0
	s_mov_b32 s8, s43
	s_mov_b64 s[2:3], s[4:5]
	s_branch .LBB0_1323

; #define LAS __attribute__((address_space(3)))
; __device__ __forceinline__ unsigned cvtpk(float lo, float hi) { f32x2v_ v = {lo, hi}; bf16x2v_ b = __builtin_convertvector(v, bf16x2v_); return __builtin_bit_cast(unsigned, b); }
; __device__ __forceinline__ void nsa_pv(f32x16& o0, f32x16& o1, const f32x16& p0, const f32x16& p1, const LAS unsigned char* vslot, int lane, int hi) {
;     u32x4 pw[4];
; #pragma unroll
;     for (int k = 0; k < 4; ++k) { pw[0][k] = cvtpk(p0[2 * k], p0[2 * k + 1]); pw[1][k] = cvtpk(p0[8 + 2 * k], p0[9 + 2 * k]); pw[2][k] = cvtpk(p1[2 * k], p1[2 * k + 1]); pw[3][k] = cvtpk(p1[8 + 2 * k], p1[9 + 2 * k]); }
;     const LAS unsigned char* vp = vslot + ((lane >> 4) & 1) * 32 + (lane & 3) * 8 + (4 * hi + ((lane & 15) >> 2)) * 64;
; #pragma unroll
;     for (int ks = 0; ks < 4; ++ks) {
;         const s16x4v a0 = __builtin_bit_cast(s16x4v, __builtin_amdgcn_ds_read_tr16_b64_v4i16((LAS s16x4v*)(vp + ks * 1024)));
;         const s16x4v a1 = __builtin_bit_cast(s16x4v, __builtin_amdgcn_ds_read_tr16_b64_v4i16((LAS s16x4v*)(vp + ks * 1024 + 512)));
;         const s16x4v b0 = __builtin_bit_cast(s16x4v, __builtin_amdgcn_ds_read_tr16_b64_v4i16((LAS s16x4v*)(vp + 4096 + ks * 1024)));
;         const s16x4v b1 = __builtin_bit_cast(s16x4v, __builtin_amdgcn_ds_read_tr16_b64_v4i16((LAS s16x4v*)(vp + 4096 + ks * 1024 + 512)));
;         const bf16x8v va = {a0[0], a0[1], a0[2], a0[3], a1[0], a1[1], a1[2], a1[3]}, vb = {b0[0], b0[1], b0[2], b0[3], b1[0], b1[1], b1[2], b1[3]};
;         const bf16x8v pa = __builtin_bit_cast(bf16x8v, pw[ks]);
;         o0 = __builtin_amdgcn_mfma_f32_32x32x16_bf16(pa, va, o0, 0, 0, 0); o1 = __builtin_amdgcn_mfma_f32_32x32x16_bf16(pa, vb, o1, 0, 0, 0); }
; }
; __device__ __forceinline__ void nsa_softmax_pv(NsaSm& st, f32x16& p0, f32x16& p1, const LAS unsigned char* vslot, LAS float* wsf, int lane, int r32, int hi, bool on = true) {
;     const float rmx = rowmax32(p0, p1); const float rm = on ? rmx : SNEG; const float mn = fmaxf(st.m, rm); const float f = __builtin_amdgcn_exp2f(st.m - mn); st.m = mn;
;     const float cs = on ? mn : 1.0e30f;
;     float s = 0.f;
; #pragma unroll
;     for (int r = 0; r < 16; ++r) { p0[r] = __builtin_amdgcn_exp2f(p0[r] - cs); p1[r] = __builtin_amdgcn_exp2f(p1[r] - cs); s += p0[r] + p1[r]; }
;     st.l = st.l * f + s;
.LBB0_1350:
	v_pk_add_f32 v[128:129], v[128:129], v[0:1] op_sel_hi:[1,0] neg_lo:[0,1] neg_hi:[0,1]
	v_pk_add_f32 v[130:131], v[130:131], v[0:1] op_sel_hi:[1,0] neg_lo:[0,1] neg_hi:[0,1]
	v_pk_add_f32 v[132:133], v[132:133], v[0:1] op_sel_hi:[1,0] neg_lo:[0,1] neg_hi:[0,1]
	v_pk_add_f32 v[134:135], v[134:135], v[0:1] op_sel_hi:[1,0] neg_lo:[0,1] neg_hi:[0,1]
	v_pk_add_f32 v[136:137], v[136:137], v[0:1] op_sel_hi:[1,0] neg_lo:[0,1] neg_hi:[0,1]
	v_pk_add_f32 v[138:139], v[138:139], v[0:1] op_sel_hi:[1,0] neg_lo:[0,1] neg_hi:[0,1]
	v_pk_add_f32 v[140:141], v[140:141], v[0:1] op_sel_hi:[1,0] neg_lo:[0,1] neg_hi:[0,1]
	v_pk_add_f32 v[142:143], v[142:143], v[0:1] op_sel_hi:[1,0] neg_lo:[0,1] neg_hi:[0,1]
	v_pk_add_f32 v[112:113], v[112:113], v[0:1] op_sel_hi:[1,0] neg_lo:[0,1] neg_hi:[0,1]
	v_pk_add_f32 v[114:115], v[114:115], v[0:1] op_sel_hi:[1,0] neg_lo:[0,1] neg_hi:[0,1]
	v_pk_add_f32 v[116:117], v[116:117], v[0:1] op_sel_hi:[1,0] neg_lo:[0,1] neg_hi:[0,1]
	v_pk_add_f32 v[118:119], v[118:119], v[0:1] op_sel_hi:[1,0] neg_lo:[0,1] neg_hi:[0,1]
	v_pk_add_f32 v[120:121], v[120:121], v[0:1] op_sel_hi:[1,0] neg_lo:[0,1] neg_hi:[0,1]
	v_pk_add_f32 v[122:123], v[122:123], v[0:1] op_sel_hi:[1,0] neg_lo:[0,1] neg_hi:[0,1]
	v_pk_add_f32 v[124:125], v[124:125], v[0:1] op_sel_hi:[1,0] neg_lo:[0,1] neg_hi:[0,1]
	v_pk_add_f32 v[126:127], v[126:127], v[0:1] op_sel_hi:[1,0] neg_lo:[0,1] neg_hi:[0,1]
	v_exp_f32_e32 v128, v128
	v_exp_f32_e32 v129, v129
	v_exp_f32_e32 v130, v130
	v_exp_f32_e32 v131, v131
	v_exp_f32_e32 v132, v132
	v_exp_f32_e32 v133, v133
	v_exp_f32_e32 v134, v134
	v_exp_f32_e32 v135, v135
	v_add_u32_e32 v3, s30, v238
	v_cvt_pk_bf16_f32 v4, v128, v129
	v_cvt_pk_bf16_f32 v5, v130, v131
	v_cvt_pk_bf16_f32 v6, v132, v133
	v_cvt_pk_bf16_f32 v7, v134, v135
	ds_read_b64_tr_b16 v[8:9], v3 offset:17408
	ds_read_b64_tr_b16 v[10:11], v3 offset:17920
	v_exp_f32_e32 v136, v136
	v_exp_f32_e32 v137, v137
	v_exp_f32_e32 v138, v138
	v_exp_f32_e32 v139, v139
	v_exp_f32_e32 v140, v140
	v_exp_f32_e32 v141, v141
	v_exp_f32_e32 v142, v142
	s_waitcnt lgkmcnt(0)
	v_mfma_f32_32x32x16_bf16 v[96:111], v[4:7], v[8:11], v[96:111]
	ds_read_b64_tr_b16 v[8:9], v3 offset:18432
	ds_read_b64_tr_b16 v[144:145], v3 offset:21504
	ds_read_b64_tr_b16 v[146:147], v3 offset:22016
	ds_read_b64_tr_b16 v[10:11], v3 offset:18944
	v_exp_f32_e32 v143, v143
	v_cvt_pk_bf16_f32 v12, v136, v137
	v_cvt_pk_bf16_f32 v13, v138, v139
	v_cvt_pk_bf16_f32 v14, v140, v141
	v_cvt_pk_bf16_f32 v15, v142, v143
	v_exp_f32_e32 v112, v112
	s_waitcnt lgkmcnt(1)
	v_mfma_f32_32x32x16_bf16 v[80:95], v[4:7], v[144:147], v[80:95]
	ds_read_b64_tr_b16 v[4:5], v3 offset:22528
	ds_read_b64_tr_b16 v[6:7], v3 offset:23040
	v_exp_f32_e32 v113, v113
	v_exp_f32_e32 v114, v114
	v_exp_f32_e32 v115, v115
	v_exp_f32_e32 v116, v116
	v_exp_f32_e32 v117, v117
	v_exp_f32_e32 v118, v118
	v_exp_f32_e32 v119, v119
	s_waitcnt lgkmcnt(2)
	v_mfma_f32_32x32x16_bf16 v[96:111], v[12:15], v[8:11], v[96:111]
	v_cvt_pk_bf16_f32 v8, v112, v113
	v_cvt_pk_bf16_f32 v9, v114, v115
	v_cvt_pk_bf16_f32 v10, v116, v117
	v_cvt_pk_bf16_f32 v11, v118, v119
	s_waitcnt lgkmcnt(0)
	v_mfma_f32_32x32x16_bf16 v[80:95], v[12:15], v[4:7], v[80:95]
	ds_read_b64_tr_b16 v[4:5], v3 offset:19456
	ds_read_b64_tr_b16 v[6:7], v3 offset:19968
	v_exp_f32_e32 v120, v120
	v_exp_f32_e32 v121, v121
	v_exp_f32_e32 v122, v122
	v_exp_f32_e32 v123, v123
	v_exp_f32_e32 v124, v124
	v_exp_f32_e32 v125, v125
	v_exp_f32_e32 v126, v126
	v_exp_f32_e32 v127, v127
	s_waitcnt lgkmcnt(0)
	v_mfma_f32_32x32x16_bf16 v[96:111], v[8:11], v[4:7], v[96:111]
	ds_read_b64_tr_b16 v[4:5], v3 offset:20480
	ds_read_b64_tr_b16 v[12:13], v3 offset:23552
	ds_read_b64_tr_b16 v[14:15], v3 offset:24064
	ds_read_b64_tr_b16 v[6:7], v3 offset:20992
	v_cvt_pk_bf16_f32 v144, v120, v121
	v_cvt_pk_bf16_f32 v145, v122, v123
	v_cvt_pk_bf16_f32 v146, v124, v125
	v_cvt_pk_bf16_f32 v147, v126, v127
	s_andn2_b64 vcc, exec, s[16:17]
	s_waitcnt lgkmcnt(1)
	v_mfma_f32_32x32x16_bf16 v[80:95], v[8:11], v[12:15], v[80:95]
	v_pk_add_f32 v[128:129], v[128:129], v[130:131]
	v_pk_add_f32 v[132:133], v[132:133], v[134:135]
	v_pk_add_f32 v[136:137], v[136:137], v[138:139]
	v_pk_add_f32 v[140:141], v[140:141], v[142:143]
	v_pk_add_f32 v[112:113], v[112:113], v[114:115]
	s_waitcnt lgkmcnt(0)
	v_mfma_f32_32x32x16_bf16 v[96:111], v[144:147], v[4:7], v[96:111]
	ds_read_b64_tr_b16 v[4:5], v3 offset:24576
	ds_read_b64_tr_b16 v[6:7], v3 offset:25088
	v_pk_add_f32 v[116:117], v[116:117], v[118:119]
	v_pk_add_f32 v[120:121], v[120:121], v[122:123]
	v_pk_add_f32 v[124:125], v[124:125], v[126:127]
	v_pk_add_f32 v[128:129], v[128:129], v[132:133]
	v_pk_add_f32 v[136:137], v[136:137], v[140:141]
	v_pk_add_f32 v[112:113], v[112:113], v[116:117]
	s_waitcnt lgkmcnt(0)
	v_mfma_f32_32x32x16_bf16 v[80:95], v[144:147], v[4:7], v[80:95]
	v_pk_add_f32 v[120:121], v[120:121], v[124:125]
	v_pk_add_f32 v[128:129], v[128:129], v[136:137]
	v_pk_add_f32 v[112:113], v[112:113], v[120:121]
	v_pk_add_f32 v[128:129], v[128:129], v[112:113]
	v_add_f32_e32 v128, v128, v129
	s_cbranch_vccnz .LBB0_1352
	s_xor_b32 s8, s30, 0x2000
	v_add_u32_e32 v3, s8, v251
	s_waitcnt vmcnt(1)
	ds_write_b128 v3, v[224:227] offset:1024
	s_waitcnt vmcnt(0)
	ds_write_b128 v3, v[228:231] offset:17408
.LBB0_1352:
	s_xor_b32 s25, s25, 1
	s_add_i32 s13, s13, -1
	s_add_i32 s24, s24, 64
	v_fma_f32 v3, v250, v2, v128
	s_cmp_gt_i32 s19, s20
	s_waitcnt lgkmcnt(0)
	s_barrier
	s_cbranch_scc0 .LBB0_1354
	v_mov_b32_e32 v250, v3
	v_mov_b32_e32 v233, v0
	s_branch .LBB0_1340
